# v21 plus work-queue index fetched one item ahead and the GLA chunk loop no longer waiting for the previous chunk's output stores
# baseline (speedup 1.0000x reference)
; #define LAS __attribute__((address_space(3)))
; template <bool RET>
; __device__ __forceinline__ void recur_item(ParamsK p, int l, int b, int h, int vs, LAS unsigned char* lds) {
;     constexpr int DV = RET ? 128 : 256, NH = RET ? 8 : 4;
;     const int tid = fresh_tid(), w = tid >> 6, lane = tid & 63, r = lane & 15, q = lane >> 4;
;     LAS float* Bc = (LAS float*)lds;
;     LAS bf16_t* Qt = (LAS bf16_t*)(lds + 32768);
;     LAS bf16_t* Kt = Qt + 64 * 136;
;     LAS bf16_t* KhT = Kt + 64 * 136;
;     LAS bf16_t* Vt = KhT + 128 * 72;
;     LAS bf16_t* Pm = Vt + 64 * 72;
;     LAS bf16_t* St = Pm + 64 * 72;
;     LAS float* Gl = (LAS float*)(St + 64 * 136);
;     LAS float* Gs = Gl + 64 * 16;
;     const bf16_t* proj = (const bf16_t*)(p->ws + WS_PROJ);
;     float* oraw = (float*)(p->ws + WS_ORAW);
;     const int qcol = (RET ? OFF_RQ : OFF_GQ) + h * 128, kcol = (RET ? OFF_RK : OFF_GK) + h * 128, vcol = (RET ? OFF_RV : OFF_GV) + h * DV + vs * 64;
;     const int ocol = (RET ? 1024 + h * 128 : h * 256) + vs * 64;
;     for (int i = tid; i < 64 * 136; i += 512) St[i] = 0;
;     const float* bcum = (const float*)(p->ws + WS_BCUM) + h * 128;
;     const float lg = log1pf(-exp2f(-5.0f - (float)h));
;     (void)Bc;
;     f32x4 accS[4];
; #pragma unroll
;     for (int i = 0; i < 4; ++i) accS[i] = (f32x4){0.f, 0.f, 0.f, 0.f};
;     u32x4 nq[2], nk[2], nv; f32x4 nb[2][2], nl[2], nd;
;     {
;         const size_t row0 = (size_t)b * SEQ;
; #pragma unroll
;         for (int i = 0; i < 2; ++i) { const int idx = tid + i * 512, t = idx >> 4, kv = (idx & 15) * 8;
;             nq[i] = *(const u32x4*)(proj + (row0 + t) * NIN + qcol + kv); nk[i] = *(const u32x4*)(proj + (row0 + t) * NIN + kcol + kv); }
;         nv = *(const u32x4*)(proj + (row0 + (tid >> 3)) * NIN + vcol + (tid & 7) * 8);
;         if (!RET) {
; #pragma unroll
;             for (int i = 0; i < 2; ++i) { const int idx = tid + i * 512, t = idx >> 4, kv = (idx & 15) * 8; nb[i][0] = *(const f32x4*)(bcum + (row0 + t) * 512 + kv); nb[i][1] = *(const f32x4*)(bcum + (row0 + t) * 512 + kv + 4); }
;             { const int kv = (tid & 15) * 8; nl[0] = *(const f32x4*)(bcum + (row0 + 63) * 512 + kv); nl[1] = *(const f32x4*)(bcum + (row0 + 63) * 512 + kv + 4); nd = *(const f32x4*)(bcum + (row0 + 63) * 512 + 16 * w + q * 4); } }
;     }
;     __syncthreads();
.LBB0_651:
	s_or_b64 exec, exec, s[4:5]
	s_ashr_i32 s16, s55, 4
	s_bfe_u32 s40, s55, 0x20002
	s_waitcnt lgkmcnt(0)
	s_add_u32 s4, s18, 0x14300000
	s_addc_u32 s5, s19, 0
	s_ashr_i32 s17, s16, 31
	v_ashrrev_i32_e32 v2, 4, v8
	s_lshl_b64 s[20:21], s[16:17], 11
	v_ashrrev_i32_e32 v3, 31, v2
	v_lshl_add_u64 v[10:11], s[20:21], 0, v[2:3]
	v_mov_b64_e32 v[12:13], s[4:5]
	s_lshl_b32 s6, s55, 6
	v_lshlrev_b32_e32 v69, 3, v8
	v_mad_u64_u32 v[4:5], s[4:5], v10, s73, v[12:13]
	s_lshl_b32 s28, s40, 8
	s_and_b32 s41, s6, 0xc0
	s_and_b32 s6, s29, 3
	v_and_b32_e32 v76, 0x78, v69
	v_mad_i32_i24 v5, v11, s73, v5
	s_mov_b32 s29, s53
	v_lshl_add_u64 v[4:5], v[4:5], 0, s[28:29]
	v_lshlrev_b32_e32 v0, 1, v76
	v_lshl_add_u64 v[4:5], v[4:5], 0, v[0:1]
	global_load_dwordx4 v[46:49], v[4:5], off offset:2048
	global_load_dwordx4 v[42:45], v[4:5], off offset:3072
	v_add_u32_e32 v4, 0x200, v8
	v_ashrrev_i32_e32 v4, 4, v4
	v_ashrrev_i32_e32 v5, 31, v4
	v_lshl_add_u64 v[14:15], s[20:21], 0, v[4:5]
	v_mad_u64_u32 v[6:7], s[4:5], v14, s73, v[12:13]
	s_lshl_b32 s6, s6, 6
	v_mad_i32_i24 v7, v15, s73, v7
	s_or_b32 s45, s28, s6
	v_lshl_add_u64 v[6:7], v[6:7], 0, s[28:29]
	s_or_b32 s44, s28, s41
	s_lshl_b32 s6, s45, 1
	v_lshl_add_u64 v[6:7], v[6:7], 0, v[0:1]
	s_lshl_b32 s8, s44, 1
	s_or_b32 s52, s6, 0x1000
	global_load_dwordx4 v[30:33], v[6:7], off offset:2048
	global_load_dwordx4 v[26:29], v[6:7], off offset:3072
	s_lshl_b32 s29, s40, 9
	v_ashrrev_i32_e32 v6, 3, v8
	s_add_u32 s4, s18, s29
	v_ashrrev_i32_e32 v7, 31, v6
	s_addc_u32 s5, s19, 0
	v_lshl_add_u64 v[16:17], s[20:21], 0, v[6:7]
	s_add_u32 s4, s4, 0x35ac4400
	v_mad_u64_u32 v[12:13], s[6:7], v16, s73, v[12:13]
	s_addc_u32 s5, s5, 0
	v_mad_i32_i24 v13, v17, s73, v13
	s_or_b32 s6, s8, 0x1000
	s_mov_b32 s7, s53
	v_and_b32_e32 v7, 56, v69
	v_lshl_add_u64 v[12:13], v[12:13], 0, s[6:7]
	v_lshlrev_b32_e32 v16, 1, v7
	v_mov_b32_e32 v17, v1
	v_lshl_add_u64 v[12:13], v[12:13], 0, v[16:17]
	v_lshlrev_b32_e32 v16, 2, v76
	s_lshl_b64 s[30:31], s[16:17], 22
	v_ashrrev_i32_e32 v9, 6, v8
	s_waitcnt vmcnt(6)
	v_lshl_add_u64 v[18:19], s[4:5], 0, v[16:17]
	s_add_u32 s4, s4, s30
	s_addc_u32 s5, s5, s31
	v_lshlrev_b32_e32 v66, 4, v9
	v_lshlrev_b64 v[10:11], 11, v[10:11]
	s_add_u32 s4, s4, 0x1f800
	v_ashrrev_i32_e32 v67, 31, v66
	v_bfe_u32 v21, v8, 4, 2
	v_lshl_add_u64 v[10:11], v[18:19], 0, v[10:11]
	global_load_dwordx4 v[22:25], v[12:13], off
	global_load_dwordx4 v[58:61], v[10:11], off
	v_lshlrev_b64 v[12:13], 11, v[14:15]
	s_addc_u32 s5, s5, 0
	v_lshlrev_b64 v[14:15], 2, v[66:67]
	v_lshl_add_u64 v[12:13], v[18:19], 0, v[12:13]
	global_load_dwordx4 v[50:53], v[10:11], off offset:16
	global_load_dwordx4 v[38:41], v[12:13], off
	global_load_dwordx4 v[54:57], v16, s[4:5] offset:16
	global_load_dwordx4 v[62:65], v16, s[4:5]
	v_lshl_add_u64 v[10:11], s[4:5], 0, v[14:15]
	v_lshlrev_b32_e32 v16, 4, v21
	v_lshl_add_u64 v[10:11], v[10:11], 0, v[16:17]
	global_load_dwordx4 v[34:37], v[12:13], off offset:16
	s_nop 0
	global_load_dwordx4 v[10:13], v[10:11], off
	v_add_u32_e32 v18, 0, v0
	v_mul_u32_u24_e32 v0, 0x90, v7
	v_bitop3_b32 v7, v69, v6, 56 bitop3:0x6c
	v_and_b32_e32 v70, 15, v8
	v_lshlrev_b32_e32 v7, 1, v7
	v_readlane_b32 s46, v252, 14
	v_mul_u32_u24_e32 v118, 0x110, v70
	v_and_b32_e32 v67, 48, v8
	v_add3_u32 v0, s46, v0, v7
	v_ashrrev_i32_e32 v7, 7, v8
	v_lshlrev_b32_e32 v72, 4, v7
	v_add3_u32 v20, 0, v118, v67
	s_movk_i32 s4, 0x1100
	v_mad_u64_u32 v[74:75], s[4:5], v7, s4, v[20:21]
	v_or_b32_e32 v71, v72, v70
	s_movk_i32 s17, 0x90
	v_readlane_b32 s5, v252, 15
	v_readlane_b32 s4, v252, 13
	v_mul_lo_u32 v71, v71, s17
	v_or_b32_e32 v75, v66, v70
	v_lshlrev_b32_e32 v68, 2, v21
	v_add3_u32 v96, s4, v118, v67
	v_and_b32_e32 v67, 8, v8
	v_lshlrev_b32_e32 v21, 3, v21
	v_add3_u32 v102, s5, v71, v16
	v_and_b32_e32 v71, 48, v66
	v_mul_lo_u32 v75, v75, s17
	v_readlane_b32 s7, v252, 16
	v_and_b32_e32 v17, 1, v9
	v_or_b32_e32 v77, v71, v67
	v_add_u32_e32 v78, s7, v75
	v_bitop3_b32 v71, v71, v21, v67 bitop3:0x36
	v_lshlrev_b32_e32 v19, 1, v17
	v_lshl_add_u32 v75, v71, 1, v78
	v_bitop3_b32 v71, v21, v77, 32 bitop3:0x36
	v_lshlrev_b32_e32 v9, 5, v9
	s_movk_i32 s6, 0x110
	v_lshl_add_u32 v81, v70, 1, s5
	v_lshl_add_u32 v71, v71, 1, v78
	v_add3_u32 v120, s4, v9, v21
	v_mul_u32_u24_e32 v97, 0x90, v76
	v_mad_u64_u32 v[78:79], s[4:5], v2, s6, v[18:19]
	v_mad_u64_u32 v[76:77], s[4:5], v4, s6, v[18:19]
	v_or_b32_e32 v18, 1, v68
	v_cmp_gt_u32_e64 s[8:9], v70, v18
	v_or_b32_e32 v18, 2, v68
	v_bitop3_b32 v9, v69, v2, 56 bitop3:0x6c
	v_bitop3_b32 v69, v4, v69, 56 bitop3:0x78
	v_cmp_gt_u32_e64 s[10:11], v70, v18
	v_or_b32_e32 v18, 3, v68
	v_lshlrev_b32_e32 v107, 4, v17
	v_lshl_add_u32 v9, v9, 1, s7
	v_lshl_add_u32 v98, v69, 1, s7
	v_cmp_eq_u32_e64 s[4:5], v19, v7
	v_cmp_gt_u32_e64 s[6:7], v70, v68
	v_cmp_gt_u32_e64 s[12:13], v70, v18
	v_or_b32_e32 v18, 1, v19
	v_cmp_gt_i32_e32 vcc, v19, v7
	s_and_b64 s[22:23], s[4:5], s[6:7]
	s_and_b64 s[24:25], s[4:5], s[8:9]
	s_and_b64 s[26:27], s[4:5], s[10:11]
	s_and_b64 s[42:43], s[4:5], s[12:13]
	v_mul_u32_u24_e32 v112, 0x1100, v18
	v_cmp_ge_i32_e64 s[14:15], v19, v7
	v_cmp_eq_u32_e64 s[4:5], v18, v7
	v_lshl_add_u32 v113, v18, 5, v81
	v_or_b32_e32 v18, v107, v70
	v_mov_b32_e32 v19, s46
	v_or_b32_e32 v82, 32, v21
	v_mad_u32_u24 v18, v18, s17, v19
	v_bitop3_b32 v69, v107, v21, v67 bitop3:0x36
	v_or_b32_e32 v7, 32, v107
	v_lshl_add_u32 v110, v69, 1, v18
	v_bitop3_b32 v69, v107, v82, v67 bitop3:0x36
	v_lshl_add_u32 v109, v69, 1, v18
	v_or_b32_e32 v18, v7, v70
	v_mul_u32_u24_e32 v121, 0x110, v7
	v_mad_u32_u24 v18, v18, s17, v19
	v_bitop3_b32 v69, v7, v21, v67 bitop3:0x36
	v_bitop3_b32 v7, v7, v82, v67 bitop3:0x36
; template <bool RET>
; __device__ __forceinline__ void recur_item(ParamsK p, int l, int b, int h, int vs, LAS unsigned char* lds) {
;     ...
;     f32x4 accS[4];
; #pragma unroll
;     for (int i = 0; i < 4; ++i) accS[i] = (f32x4){0.f, 0.f, 0.f, 0.f};
;     u32x4 nq[2], nk[2], nv; f32x4 nb[2][2], nl[2], nd;
;     {
;         const size_t row0 = (size_t)b * SEQ;
; #pragma unroll
;         for (int i = 0; i < 2; ++i) { const int idx = tid + i * 512, t = idx >> 4, kv = (idx & 15) * 8;
;             nq[i] = *(const u32x4*)(proj + (row0 + t) * NIN + qcol + kv); nk[i] = *(const u32x4*)(proj + (row0 + t) * NIN + kcol + kv); }
;         nv = *(const u32x4*)(proj + (row0 + (tid >> 3)) * NIN + vcol + (tid & 7) * 8);
;         if (!RET) {
; #pragma unroll
;             for (int i = 0; i < 2; ++i) { const int idx = tid + i * 512, t = idx >> 4, kv = (idx & 15) * 8; nb[i][0] = *(const f32x4*)(bcum + (row0 + t) * 512 + kv); nb[i][1] = *(const f32x4*)(bcum + (row0 + t) * 512 + kv + 4); }
;             { const int kv = (tid & 15) * 8; nl[0] = *(const f32x4*)(bcum + (row0 + 63) * 512 + kv); nl[1] = *(const f32x4*)(bcum + (row0 + 63) * 512 + kv + 4); nd = *(const f32x4*)(bcum + (row0 + 63) * 512 + 16 * w + q * 4); } }
;     }
;     __syncthreads();
;     for (int c = 0; c < 32; ++c) {
;         const size_t row0 = (size_t)b * SEQ + c * 64;
; #pragma unroll
;         for (int i = 0; i < 2; ++i) {
;             const int idx = tid + i * 512, t = idx >> 4, kv = (idx & 15) * 8;
;             float bb[8], bl[8];
;             if (RET) {
; #pragma unroll
;                 for (int j = 0; j < 8; ++j) { bb[j] = (float)(t + 1) * lg; bl[j] = 64.0f * lg; }
;             } else {
;                 const f32x4 b0 = nb[i][0], b1 = nb[i][1], l0 = nl[0], l1 = nl[1];
;                 bb[0] = b0[0]; bb[1] = b0[1]; bb[2] = b0[2]; bb[3] = b0[3]; bb[4] = b1[0]; bb[5] = b1[1]; bb[6] = b1[2]; bb[7] = b1[3];
;                 bl[0] = l0[0]; bl[1] = l0[1]; bl[2] = l0[2]; bl[3] = l0[3]; bl[4] = l1[0]; bl[5] = l1[1]; bl[6] = l1[2]; bl[7] = l1[3];
;             }
;             float qf[8] = {bflo(nq[i].x), bfhi(nq[i].x), bflo(nq[i].y), bfhi(nq[i].y), bflo(nq[i].z), bfhi(nq[i].z), bflo(nq[i].w), bfhi(nq[i].w)};
;             float kf[8] = {bflo(nk[i].x), bfhi(nk[i].x), bflo(nk[i].y), bfhi(nk[i].y), bflo(nk[i].z), bfhi(nk[i].z), bflo(nk[i].w), bfhi(nk[i].w)};
;             float qt[8], kt[8];
; #pragma unroll
	v_lshl_add_u32 v103, v69, 1, v18
	v_lshl_add_u32 v104, v7, 1, v18
	v_mad_u32_u24 v7, v70, s17, v19
	v_bitop3_b32 v18, v21, v8, 8 bitop3:0x78
	v_lshl_add_u32 v106, v18, 1, v7
	v_bitop3_b32 v18, v21, v67, 32 bitop3:0x36
	v_lshl_add_u32 v105, v18, 1, v7
	v_or_b32_e32 v18, 16, v67
	v_or_b32_e32 v19, 16, v70
	v_add_u32_e32 v69, 0x900, v7
	v_bitop3_b32 v18, v21, v18, 32 bitop3:0x36
	v_lshl_add_u32 v100, v18, 1, v69
	v_mul_u32_u24_e32 v122, 0x110, v19
	v_add_u32_e32 v18, 0x1200, v7
	v_bitop3_b32 v19, v21, v67, 32 bitop3:0x1e
	v_bitop3_b32 v77, v21, v67, 16 bitop3:0x1e
	v_lshl_add_u32 v79, v19, 1, v18
	v_bitop3_b32 v19, v21, v67, 32 bitop3:0x14
	v_lshl_add_u32 v101, v77, 1, v69
	v_lshl_add_u32 v77, v19, 1, v18
	v_or_b32_e32 v18, 48, v67
	v_add_u32_e32 v7, 0x1b00, v7
	v_bitop3_b32 v19, v21, v67, 48 bitop3:0x1e
	v_bitop3_b32 v18, v21, v18, 32 bitop3:0x36
	v_ashrrev_i32_e32 v73, 31, v72
	v_lshl_add_u32 v69, v19, 1, v7
	v_lshl_add_u32 v67, v18, 1, v7
	v_or_b32_e32 v18, s20, v68
	v_mov_b32_e32 v19, s21
	v_or_b32_e32 v80, v68, v72
	v_lshlrev_b32_e32 v83, 6, v17
	v_lshl_add_u64 v[18:19], v[18:19], 0, v[72:73]
	v_add_u32_e32 v108, v81, v83
	v_mul_lo_u32 v111, v80, s17
	s_and_b64 s[6:7], s[4:5], s[6:7]
	v_lshlrev_b64 v[80:81], 13, v[18:19]
	s_mul_i32 s17, s16, 0x3900000
	s_and_b64 s[8:9], s[4:5], s[8:9]
	s_and_b64 s[10:11], s[4:5], s[10:11]
	s_and_b64 s[12:13], s[4:5], s[12:13]
	s_or_b64 s[4:5], vcc, s[22:23]
	s_or_b64 s[22:23], vcc, s[24:25]
	s_or_b64 s[24:25], vcc, s[26:27]
	s_or_b64 s[26:27], vcc, s[42:43]
	s_or_b64 vcc, s[14:15], s[6:7]
	v_or_b32_e32 v7, v80, v83
	v_or_b32_e32 v18, s45, v70
	s_mul_hi_i32 s7, s16, 0x3900000
	s_or_b32 s6, s17, s28
	s_or_b64 s[8:9], s[14:15], s[8:9]
	s_or_b64 s[10:11], s[14:15], s[10:11]
	s_or_b64 s[12:13], s[14:15], s[12:13]
	v_lshl_or_b32 v80, v18, 2, v7
	v_mov_b64_e32 v[18:19], s[6:7]
	s_or_b32 s6, s30, s29
	v_mad_i64_i32 v[82:83], s[14:15], v2, s73, v[18:19]
	s_add_u32 s6, s6, 0x35b03c00
	s_addc_u32 s14, s31, 0
	v_or_b32_e32 v84, s6, v16
	v_mov_b32_e32 v85, s14
	v_lshlrev_b32_e32 v16, 5, v70
	v_lshl_add_u64 v[86:87], v[84:85], 0, v[14:15]
	v_or_b32_e32 v84, s6, v16
	s_add_u32 s6, s17, 0x144c8000
	s_addc_u32 s7, s7, 0
	v_mov_b64_e32 v[14:15], s[6:7]
	v_mad_i64_i32 v[6:7], s[6:7], v6, s73, v[14:15]
	v_and_b32_e32 v8, 7, v8
	v_lshl_or_b32 v6, v8, 4, v6
	v_lshl_add_u64 v[88:89], v[6:7], 0, s[52:53]
	v_lshlrev_b64 v[6:7], 11, v[4:5]
	v_lshlrev_b64 v[2:3], 11, v[2:3]
	v_mul_u32_u24_e32 v99, 0x2200, v17
	v_mul_u32_u24_e32 v17, 0x1100, v17
	v_lshlrev_b32_e32 v21, 4, v70
	v_lshl_add_u64 v[90:91], s[30:31], 0, v[6:7]
	v_mad_i64_i32 v[92:93], s[6:7], v4, s73, v[18:19]
	v_lshl_add_u64 v[94:95], s[30:31], 0, v[2:3]
	v_mov_b32_e32 v2, 0
	v_or_b32_e32 v82, v82, v21
	v_or3_b32 v90, v90, s29, v16
	v_or_b32_e32 v92, v92, v21
	v_or3_b32 v94, v94, s29, v16
	s_mov_b32 s14, 31
	v_add_u32_e32 v119, v9, v97
	v_add_u32_e32 v117, v98, v97
	v_add_u32_e32 v116, v20, v99
	v_add_u32_e32 v115, v108, v111
	v_add_u32_e32 v114, v20, v112
	v_add_u32_e32 v113, v113, v111
	v_add_u32_e32 v112, v96, v17
	v_add_u32_e32 v111, v96, v121
	v_add_u32_e32 v108, v120, v122
	v_mov_b32_e32 v3, v2
	v_mov_b32_e32 v4, v2
	v_mov_b32_e32 v5, v2
	v_mov_b32_e32 v6, v2
	v_mov_b32_e32 v7, v2
	v_mov_b32_e32 v8, v2
	v_mov_b32_e32 v9, v2
	v_mov_b32_e32 v14, v2
	v_mov_b32_e32 v15, v2
	v_mov_b32_e32 v16, v2
	v_mov_b32_e32 v17, v2
	v_mov_b32_e32 v18, v2
	v_mov_b32_e32 v19, v2
	v_mov_b32_e32 v20, v2
	v_mov_b32_e32 v21, v2
	s_waitcnt vmcnt(0)
	s_barrier
.LBB0_652:
	s_waitcnt vmcnt(9)
	v_mul_f32_e32 v62, 0x3fb8aa3b, v62
	v_mul_f32_e32 v96, 0xbfb8aa3b, v58
	v_mul_f32_e32 v58, 0x3fb8aa3b, v58
	v_exp_f32_e32 v121, v62
	v_mul_f32_e32 v62, 0xbfb8aa3b, v59
	v_mul_f32_e32 v59, 0x3fb8aa3b, v59
	v_exp_f32_e32 v58, v58
	v_exp_f32_e32 v59, v59
	v_exp_f32_e32 v96, v96
	v_exp_f32_e32 v97, v62
	v_lshlrev_b32_e32 v98, 16, v46
	v_and_b32_e32 v99, 0xffff0000, v46
	v_pk_mul_f32 v[58:59], v[58:59], v[98:99]
	v_lshlrev_b32_e32 v98, 16, v42
	v_and_b32_e32 v99, 0xffff0000, v42
	v_pk_mul_f32 v[96:97], v[96:97], v[98:99]
	v_lshlrev_b32_e32 v46, 16, v47
	v_mul_f32_e32 v42, v96, v121
	v_cvt_pk_bf16_f32 v42, v42, s0
	ds_write_b16 v119, v42
	v_mul_f32_e32 v42, 0x3fb8aa3b, v63
	v_exp_f32_e32 v98, v42
	v_and_b32_e32 v47, 0xffff0000, v47
	s_waitcnt vmcnt(8)
; #define LAS __attribute__((address_space(3)))
; template <bool RET>
; __device__ __forceinline__ void recur_item(ParamsK p, int l, int b, int h, int vs, LAS unsigned char* lds) {
;     ...
; #pragma unroll
;         for (int i = 0; i < 2; ++i) {
;             const int idx = tid + i * 512, t = idx >> 4, kv = (idx & 15) * 8;
;             float bb[8], bl[8];
;             if (RET) {
; #pragma unroll
;                 for (int j = 0; j < 8; ++j) { bb[j] = (float)(t + 1) * lg; bl[j] = 64.0f * lg; }
;             } else {
;                 const f32x4 b0 = nb[i][0], b1 = nb[i][1], l0 = nl[0], l1 = nl[1];
;                 bb[0] = b0[0]; bb[1] = b0[1]; bb[2] = b0[2]; bb[3] = b0[3]; bb[4] = b1[0]; bb[5] = b1[1]; bb[6] = b1[2]; bb[7] = b1[3];
;                 bl[0] = l0[0]; bl[1] = l0[1]; bl[2] = l0[2]; bl[3] = l0[3]; bl[4] = l1[0]; bl[5] = l1[1]; bl[6] = l1[2]; bl[7] = l1[3];
;             }
;             float qf[8] = {bflo(nq[i].x), bfhi(nq[i].x), bflo(nq[i].y), bfhi(nq[i].y), bflo(nq[i].z), bfhi(nq[i].z), bflo(nq[i].w), bfhi(nq[i].w)};
;             float kf[8] = {bflo(nk[i].x), bfhi(nk[i].x), bflo(nk[i].y), bfhi(nk[i].y), bflo(nk[i].z), bfhi(nk[i].z), bflo(nk[i].w), bfhi(nk[i].w)};
;             float qt[8], kt[8];
; #pragma unroll
;             for (int j = 0; j < 8; ++j) { const float em = __expf(-bb[j]); qt[j] = qf[j] * __expf(bb[j]); kt[j] = kf[j] * em; KhT[(kv + j) * 72 + (t ^ (((kv >> 3) & 7) << 3))] = f2bf(kt[j] * __expf(bl[j])); }
;             u32x4 wq, wk;
;             wq.x = cvt_pk_bf16(qt[0], qt[1]); wq.y = cvt_pk_bf16(qt[2], qt[3]); wq.z = cvt_pk_bf16(qt[4], qt[5]); wq.w = cvt_pk_bf16(qt[6], qt[7]);
;             wk.x = cvt_pk_bf16(kt[0], kt[1]); wk.y = cvt_pk_bf16(kt[2], kt[3]); wk.z = cvt_pk_bf16(kt[4], kt[5]); wk.w = cvt_pk_bf16(kt[6], kt[7]);
;             *(LAS u32x4*)(Qt + t * 136 + kv) = wq; *(LAS u32x4*)(Kt + t * 136 + kv) = wk;
;         }
;         { const int t = tid >> 3, vv = (tid & 7) * 8; LAS bf16_t* vp = Vt + vv * 72 + (t ^ (((vv >> 3) & 7) << 3));
;             vp[0 * 72] = (bf16_t)(nv.x & 0xffffu); vp[1 * 72] = (bf16_t)(nv.x >> 16); vp[2 * 72] = (bf16_t)(nv.y & 0xffffu); vp[3 * 72] = (bf16_t)(nv.y >> 16);
;             vp[4 * 72] = (bf16_t)(nv.z & 0xffffu); vp[5 * 72] = (bf16_t)(nv.z >> 16); vp[6 * 72] = (bf16_t)(nv.w & 0xffffu); vp[7 * 72] = (bf16_t)(nv.w >> 16); }
	v_mul_f32_e32 v10, 0x3fb8aa3b, v10
	s_add_i32 s14, s14, -1
	v_mul_f32_e32 v42, v97, v98
	v_cvt_pk_bf16_f32 v42, v42, s0
	ds_write_b16 v119, v42 offset:144
	v_mul_f32_e32 v42, 0xbfb8aa3b, v60
	v_exp_f32_e32 v62, v42
	v_mul_f32_e32 v42, 0x3fb8aa3b, v60
	v_exp_f32_e32 v60, v42
	v_mul_f32_e32 v42, 0x3fb8aa3b, v64
	v_exp_f32_e32 v64, v42
	v_mul_f32_e32 v42, 0xbfb8aa3b, v61
	v_exp_f32_e32 v63, v42
	v_mul_f32_e32 v42, 0x3fb8aa3b, v61
	v_exp_f32_e32 v61, v42
	v_lshlrev_b32_e32 v42, 16, v43
	v_and_b32_e32 v43, 0xffff0000, v43
	s_cmp_eq_u32 s14, 0
	v_pk_mul_f32 v[46:47], v[60:61], v[46:47]
	v_pk_mul_f32 v[60:61], v[62:63], v[42:43]
	v_mul_f32_e32 v43, 0x3fb8aa3b, v50
	v_mul_f32_e32 v42, v60, v64
	v_cvt_pk_bf16_f32 v42, v42, s0
	ds_write_b16 v119, v42 offset:288
	v_mul_f32_e32 v42, 0x3fb8aa3b, v65
	v_exp_f32_e32 v65, v42
	v_lshlrev_b32_e32 v62, 16, v48
	v_and_b32_e32 v63, 0xffff0000, v48
	v_lshlrev_b32_e32 v48, 16, v49
	v_mul_f32_e32 v42, v61, v65
	v_cvt_pk_bf16_f32 v42, v42, s0
	ds_write_b16 v119, v42 offset:432
	v_mul_f32_e32 v42, 0xbfb8aa3b, v50
	v_exp_f32_e32 v50, v43
	v_mul_f32_e32 v43, 0x3fb8aa3b, v54
	v_exp_f32_e32 v54, v43
	v_mul_f32_e32 v43, 0xbfb8aa3b, v51
	v_mul_f32_e32 v51, 0x3fb8aa3b, v51
	v_exp_f32_e32 v51, v51
	v_exp_f32_e32 v42, v42
	v_exp_f32_e32 v43, v43
	v_and_b32_e32 v49, 0xffff0000, v49
	v_pk_mul_f32 v[50:51], v[50:51], v[62:63]
	v_lshlrev_b32_e32 v62, 16, v44
	v_and_b32_e32 v63, 0xffff0000, v44
	v_pk_mul_f32 v[62:63], v[42:43], v[62:63]
	v_mul_f32_e32 v43, 0x3fb8aa3b, v52
	v_mul_f32_e32 v42, v62, v54
	v_cvt_pk_bf16_f32 v42, v42, s0
	ds_write_b16 v119, v42 offset:576
	v_mul_f32_e32 v42, 0x3fb8aa3b, v55
	v_exp_f32_e32 v55, v42
	v_mul_f32_e32 v44, 0x3fb8aa3b, v53
	v_mul_f32_e32 v42, v63, v55
	v_cvt_pk_bf16_f32 v42, v42, s0
	ds_write_b16 v119, v42 offset:720
	v_mul_f32_e32 v42, 0xbfb8aa3b, v52
	v_exp_f32_e32 v52, v43
	v_mul_f32_e32 v43, 0x3fb8aa3b, v56
	v_exp_f32_e32 v56, v43
	v_mul_f32_e32 v43, 0xbfb8aa3b, v53
	v_exp_f32_e32 v42, v42
	v_exp_f32_e32 v43, v43
	v_exp_f32_e32 v53, v44
	v_lshlrev_b32_e32 v44, 16, v45
	v_and_b32_e32 v45, 0xffff0000, v45
	v_pk_mul_f32 v[48:49], v[52:53], v[48:49]
	v_pk_mul_f32 v[52:53], v[42:43], v[44:45]
	v_cvt_pk_bf16_f32 v43, v46, v47
	v_mul_f32_e32 v42, v52, v56
	v_cvt_pk_bf16_f32 v42, v42, s0
	ds_write_b16 v119, v42 offset:864
	v_mul_f32_e32 v42, 0x3fb8aa3b, v57
	v_exp_f32_e32 v57, v42
	v_cvt_pk_bf16_f32 v44, v50, v51
	v_cvt_pk_bf16_f32 v45, v48, v49
	v_cvt_pk_bf16_f32 v46, v96, v97
	v_mul_f32_e32 v42, v53, v57
	v_cvt_pk_bf16_f32 v42, v42, s0
	ds_write_b16 v119, v42 offset:1008
	v_cvt_pk_bf16_f32 v42, v58, v59
	v_cvt_pk_bf16_f32 v47, v60, v61
	v_cvt_pk_bf16_f32 v48, v62, v63
	v_cvt_pk_bf16_f32 v49, v52, v53
	ds_write_b128 v78, v[42:45] offset:32768
	ds_write_b128 v78, v[46:49] offset:50176
	v_mul_f32_e32 v42, 0xbfb8aa3b, v38
	v_mul_f32_e32 v38, 0x3fb8aa3b, v38
	v_mul_f32_e32 v43, 0xbfb8aa3b, v39
	v_mul_f32_e32 v39, 0x3fb8aa3b, v39
	v_exp_f32_e32 v38, v38
	v_exp_f32_e32 v39, v39
	v_exp_f32_e32 v42, v42
	v_exp_f32_e32 v43, v43
	v_lshlrev_b32_e32 v44, 16, v30
	v_and_b32_e32 v45, 0xffff0000, v30
	v_pk_mul_f32 v[38:39], v[38:39], v[44:45]
	v_lshlrev_b32_e32 v44, 16, v26
	v_and_b32_e32 v45, 0xffff0000, v26
	v_pk_mul_f32 v[42:43], v[42:43], v[44:45]
	v_lshlrev_b32_e32 v30, 16, v31
	v_mul_f32_e32 v26, v42, v121
	v_cvt_pk_bf16_f32 v26, v26, s0
	ds_write_b16 v117, v26
	v_mul_f32_e32 v26, v43, v98
	v_cvt_pk_bf16_f32 v26, v26, s0
	ds_write_b16 v117, v26 offset:144
	v_mul_f32_e32 v26, 0xbfb8aa3b, v40
	v_exp_f32_e32 v44, v26
	v_mul_f32_e32 v26, 0x3fb8aa3b, v40
	v_exp_f32_e32 v40, v26
	v_mul_f32_e32 v26, 0xbfb8aa3b, v41
	v_exp_f32_e32 v45, v26
	v_mul_f32_e32 v26, 0x3fb8aa3b, v41
	v_exp_f32_e32 v41, v26
	v_and_b32_e32 v31, 0xffff0000, v31
	v_lshlrev_b32_e32 v26, 16, v27
	v_and_b32_e32 v27, 0xffff0000, v27
	v_pk_mul_f32 v[30:31], v[40:41], v[30:31]
	v_pk_mul_f32 v[40:41], v[44:45], v[26:27]
	v_mul_f32_e32 v27, 0x3fb8aa3b, v34
	v_mul_f32_e32 v26, v40, v64
	v_cvt_pk_bf16_f32 v26, v26, s0
	ds_write_b16 v117, v26 offset:288
	v_mul_f32_e32 v26, v41, v65
	v_cvt_pk_bf16_f32 v26, v26, s0
	ds_write_b16 v117, v26 offset:432
	v_mul_f32_e32 v26, 0xbfb8aa3b, v34
	v_exp_f32_e32 v34, v27
	v_mul_f32_e32 v27, 0xbfb8aa3b, v35
	v_mul_f32_e32 v35, 0x3fb8aa3b, v35
	v_exp_f32_e32 v35, v35
	v_exp_f32_e32 v26, v26
	v_exp_f32_e32 v27, v27
	v_lshlrev_b32_e32 v44, 16, v32
	v_and_b32_e32 v45, 0xffff0000, v32
	v_pk_mul_f32 v[34:35], v[34:35], v[44:45]
	v_lshlrev_b32_e32 v44, 16, v28
	v_and_b32_e32 v45, 0xffff0000, v28
	v_pk_mul_f32 v[44:45], v[26:27], v[44:45]
	v_mul_f32_e32 v27, 0x3fb8aa3b, v36
	v_mul_f32_e32 v26, v44, v54
	v_cvt_pk_bf16_f32 v26, v26, s0
	ds_write_b16 v117, v26 offset:576
	v_mul_f32_e32 v26, v45, v55
	v_cvt_pk_bf16_f32 v26, v26, s0
	ds_write_b16 v117, v26 offset:720
	v_mul_f32_e32 v26, 0xbfb8aa3b, v36
	v_exp_f32_e32 v36, v27
	v_mul_f32_e32 v27, 0xbfb8aa3b, v37
	v_mul_f32_e32 v28, 0x3fb8aa3b, v37
	v_exp_f32_e32 v26, v26
	v_exp_f32_e32 v27, v27
	v_exp_f32_e32 v37, v28
	v_lshlrev_b32_e32 v32, 16, v33
	v_and_b32_e32 v33, 0xffff0000, v33
	v_lshlrev_b32_e32 v28, 16, v29
	v_and_b32_e32 v29, 0xffff0000, v29
	v_pk_mul_f32 v[32:33], v[36:37], v[32:33]
	v_pk_mul_f32 v[36:37], v[26:27], v[28:29]
	v_exp_f32_e32 v96, v10
	v_mul_f32_e32 v26, v36, v56
	v_mul_f32_e32 v10, 0x3fb8aa3b, v11
	v_cvt_pk_bf16_f32 v26, v26, s0
	v_exp_f32_e32 v97, v10
	v_mul_f32_e32 v10, 0x3fb8aa3b, v12
	ds_write_b16 v117, v26 offset:864
	v_mul_f32_e32 v26, v37, v57
	v_exp_f32_e32 v98, v10
	v_mul_f32_e32 v10, 0x3fb8aa3b, v13
	v_cvt_pk_bf16_f32 v26, v26, s0
	v_exp_f32_e32 v99, v10
	v_lshl_add_u64 v[10:11], s[18:19], 0, v[82:83]
	ds_write_b16 v117, v26 offset:1008
; #define LAS __attribute__((address_space(3)))
; template <bool RET>
; __device__ __forceinline__ void recur_item(ParamsK p, int l, int b, int h, int vs, LAS unsigned char* lds) {
;     ...
;         { const int t = tid >> 3, vv = (tid & 7) * 8; LAS bf16_t* vp = Vt + vv * 72 + (t ^ (((vv >> 3) & 7) << 3));
;             vp[0 * 72] = (bf16_t)(nv.x & 0xffffu); vp[1 * 72] = (bf16_t)(nv.x >> 16); vp[2 * 72] = (bf16_t)(nv.y & 0xffffu); vp[3 * 72] = (bf16_t)(nv.y >> 16);
;             vp[4 * 72] = (bf16_t)(nv.z & 0xffffu); vp[5 * 72] = (bf16_t)(nv.z >> 16); vp[6 * 72] = (bf16_t)(nv.w & 0xffffu); vp[7 * 72] = (bf16_t)(nv.w >> 16); }
;         const f32x4 dec = RET ? (f32x4){__expf(64.0f * lg), __expf(64.0f * lg), __expf(64.0f * lg), __expf(64.0f * lg)} : (f32x4){__expf(nd[0]), __expf(nd[1]), __expf(nd[2]), __expf(nd[3])};
;         if (c + 1 < 32) {
;             const size_t rn = row0 + 64;
; #pragma unroll
;             for (int i = 0; i < 2; ++i) { const int idx = tid + i * 512, t = idx >> 4, kv = (idx & 15) * 8;
;                 nq[i] = *(const u32x4*)(proj + (rn + t) * NIN + qcol + kv); nk[i] = *(const u32x4*)(proj + (rn + t) * NIN + kcol + kv); }
;             nv = *(const u32x4*)(proj + (rn + (tid >> 3)) * NIN + vcol + (tid & 7) * 8);
;             if (!RET) {
; #pragma unroll
;                 for (int i = 0; i < 2; ++i) { const int idx = tid + i * 512, t = idx >> 4, kv = (idx & 15) * 8; nb[i][0] = *(const f32x4*)(bcum + (rn + t) * 512 + kv); nb[i][1] = *(const f32x4*)(bcum + (rn + t) * 512 + kv + 4); }
;                 { const int kv = (tid & 15) * 8; nl[0] = *(const f32x4*)(bcum + (rn + 63) * 512 + kv); nl[1] = *(const f32x4*)(bcum + (rn + 63) * 512 + kv + 4); nd = *(const f32x4*)(bcum + (rn + 63) * 512 + 16 * w + q * 4); } }
;         }
;         __syncthreads();
;         const int tm = w >> 1, vb = w & 1;
; #pragma unroll
;         for (int s2 = 0; s2 < 2; ++s2) {
;             const int sn = (w & 1) * 2 + s2;
;             f32x4 sc = mma_lds((f32x4){0.f, 0.f, 0.f, 0.f}, Qt + tm * 16 * 136, 136, Kt + sn * 16 * 136, 136, 128, lane);
; #pragma unroll
;             for (int j = 0; j < 4; ++j) if (sn > tm || (sn == tm && r > q * 4 + j)) sc[j] = 0.f;
; #pragma unroll
;             for (int j = 0; j < 4; ++j) Pm[(tm * 16 + q * 4 + j) * 72 + sn * 16 + r] = f2bf(sc[j]);
;         }
;         f32x4 acco[2];
; #pragma unroll
	v_cvt_pk_bf16_f32 v26, v38, v39
	v_cvt_pk_bf16_f32 v27, v30, v31
	v_cvt_pk_bf16_f32 v28, v34, v35
	v_cvt_pk_bf16_f32 v29, v32, v33
	v_add_co_u32_e64 v10, s[6:7], s75, v10
	v_cvt_pk_bf16_f32 v30, v42, v43
	v_cvt_pk_bf16_f32 v31, v40, v41
	v_cvt_pk_bf16_f32 v32, v44, v45
	v_cvt_pk_bf16_f32 v33, v36, v37
	ds_write_b128 v76, v[26:29] offset:32768
	ds_write_b128 v76, v[30:33] offset:50176
	ds_write_b16 v0, v22
	ds_write_b16_d16_hi v0, v22 offset:144
	ds_write_b16 v0, v23 offset:288
	ds_write_b16_d16_hi v0, v23 offset:432
	ds_write_b16 v0, v24 offset:576
	ds_write_b16_d16_hi v0, v24 offset:720
	ds_write_b16 v0, v25 offset:864
	ds_write_b16_d16_hi v0, v25 offset:1008
	v_addc_co_u32_e64 v11, s[6:7], 0, v11, s[6:7]
	global_load_dwordx4 v[46:49], v[10:11], off offset:2048
	global_load_dwordx4 v[42:45], v[10:11], off offset:3072
	v_lshl_add_u64 v[10:11], s[18:19], 0, v[92:93]
	v_add_co_u32_e64 v10, s[6:7], s75, v10
	v_pk_mul_f32 v[20:21], v[20:21], v[98:99]
	s_nop 0
	v_addc_co_u32_e64 v11, s[6:7], 0, v11, s[6:7]
	global_load_dwordx4 v[30:33], v[10:11], off offset:2048
	global_load_dwordx4 v[26:29], v[10:11], off offset:3072
	v_lshl_add_u64 v[10:11], s[18:19], 0, v[88:89]
	global_load_dwordx4 v[22:25], v[10:11], off
	v_lshl_add_u64 v[10:11], s[18:19], 0, v[94:95]
	v_lshl_add_u64 v[12:13], v[10:11], 0, s[78:79]
	v_add_co_u32_e64 v10, s[6:7], s93, v10
	v_pk_mul_f32 v[18:19], v[18:19], v[96:97]
	s_nop 0
	v_addc_co_u32_e64 v11, s[6:7], 0, v11, s[6:7]
	global_load_dwordx4 v[58:61], v[10:11], off offset:1024
	global_load_dwordx4 v[50:53], v[12:13], off offset:16
	v_lshl_add_u64 v[10:11], s[18:19], 0, v[90:91]
	v_lshl_add_u64 v[12:13], v[10:11], 0, s[78:79]
	v_add_co_u32_e64 v10, s[6:7], s93, v10
	v_pk_mul_f32 v[16:17], v[16:17], v[98:99]
	s_nop 0
	v_addc_co_u32_e64 v11, s[6:7], 0, v11, s[6:7]
	global_load_dwordx4 v[38:41], v[10:11], off offset:1024
	global_load_dwordx4 v[34:37], v[12:13], off offset:16
	v_lshl_add_u64 v[10:11], s[18:19], 0, v[84:85]
	global_load_dwordx4 v[54:57], v[10:11], off offset:16
	global_load_dwordx4 v[62:65], v[10:11], off
	v_lshl_add_u64 v[10:11], s[18:19], 0, v[86:87]
	global_load_dwordx4 v[10:13], v[10:11], off
	s_waitcnt lgkmcnt(0)
	s_barrier
	ds_read_b128 v[122:125], v74 offset:32768
	ds_read_b128 v[126:129], v116 offset:50176
	s_waitcnt lgkmcnt(0)
	v_mfma_f32_16x16x32_bf16 v[122:125], v[122:125], v[126:129], 0
	ds_read_b128 v[126:129], v74 offset:32832
	ds_read_b128 v[130:133], v116 offset:50240
	s_mov_b32 s6, 0x23ea0000
	v_pk_mul_f32 v[14:15], v[14:15], v[96:97]
	s_waitcnt lgkmcnt(0)
	v_mfma_f32_16x16x32_bf16 v[122:125], v[126:129], v[130:133], v[122:125]
	ds_read_b128 v[126:129], v74 offset:32896
	ds_read_b128 v[130:133], v116 offset:50304
	v_pk_mul_f32 v[8:9], v[8:9], v[98:99]
	v_pk_mul_f32 v[6:7], v[6:7], v[96:97]
	s_waitcnt lgkmcnt(0)
	v_mfma_f32_16x16x32_bf16 v[122:125], v[126:129], v[130:133], v[122:125]
	ds_read_b128 v[126:129], v74 offset:32960
	ds_read_b128 v[130:133], v116 offset:50368
	v_pk_mul_f32 v[4:5], v[4:5], v[98:99]
	v_pk_mul_f32 v[2:3], v[2:3], v[96:97]
	s_waitcnt lgkmcnt(0)
	v_mfma_f32_16x16x32_bf16 v[122:125], v[126:129], v[130:133], v[122:125]
	v_mov_b32_e32 v126, s53
	v_lshl_add_u64 v[82:83], v[82:83], 0, s[80:81]
	v_lshl_add_u64 v[86:87], v[86:87], 0, s[82:83]
	s_nop 4
	v_cndmask_b32_e64 v121, v122, v126, s[4:5]
	v_cndmask_b32_e64 v122, v123, 0, s[22:23]
	v_cvt_pk_bf16_f32 v121, v121, s0
	v_cndmask_b32_e64 v123, v124, 0, s[24:25]
	ds_write_b16 v115, v121
	v_cvt_pk_bf16_f32 v121, v122, s0
	v_cndmask_b32_e64 v124, v125, 0, s[26:27]
	ds_write_b16 v115, v121 offset:144
	v_cvt_pk_bf16_f32 v121, v123, s0
	ds_write_b16 v115, v121 offset:288
	v_cvt_pk_bf16_f32 v121, v124, s0
	ds_write_b16 v115, v121 offset:432
	ds_read_b128 v[122:125], v74 offset:32768
	ds_read_b128 v[126:129], v114 offset:50176
	s_waitcnt lgkmcnt(0)
	v_mfma_f32_16x16x32_bf16 v[122:125], v[122:125], v[126:129], 0
	ds_read_b128 v[126:129], v74 offset:32832
	ds_read_b128 v[130:133], v114 offset:50240
	v_lshl_add_u64 v[84:85], v[84:85], 0, s[82:83]
	v_lshl_add_u64 v[88:89], v[88:89], 0, s[80:81]
	s_waitcnt lgkmcnt(0)
	v_mfma_f32_16x16x32_bf16 v[122:125], v[126:129], v[130:133], v[122:125]
	ds_read_b128 v[126:129], v74 offset:32896
	ds_read_b128 v[130:133], v114 offset:50304
	v_lshl_add_u64 v[90:91], v[90:91], 0, s[82:83]
	v_lshl_add_u64 v[92:93], v[92:93], 0, s[80:81]
	s_waitcnt lgkmcnt(0)
	v_mfma_f32_16x16x32_bf16 v[122:125], v[126:129], v[130:133], v[122:125]
	ds_read_b128 v[126:129], v74 offset:32960
	ds_read_b128 v[130:133], v114 offset:50368
	v_lshl_add_u64 v[94:95], v[94:95], 0, s[82:83]
	s_waitcnt lgkmcnt(0)
	v_mfma_f32_16x16x32_bf16 v[122:125], v[126:129], v[130:133], v[122:125]
	v_mov_b32_e32 v126, s53
	s_nop 6
	v_cndmask_b32_e32 v121, v122, v126, vcc
	v_cndmask_b32_e64 v122, v123, 0, s[8:9]
	v_cvt_pk_bf16_f32 v121, v121, s0
	v_cndmask_b32_e64 v123, v124, 0, s[10:11]
	ds_write_b16 v113, v121
	v_cvt_pk_bf16_f32 v121, v122, s0
	v_cndmask_b32_e64 v124, v125, 0, s[12:13]
	ds_write_b16 v113, v121 offset:144
	v_cvt_pk_bf16_f32 v121, v123, s0
	ds_write_b16 v113, v121 offset:288
	v_cvt_pk_bf16_f32 v121, v124, s0
	ds_write_b16 v113, v121 offset:432
	ds_read_b128 v[122:125], v74 offset:32768
	ds_read_b128 v[126:129], v74 offset:32832
	ds_read_b128 v[130:133], v74 offset:32896
	ds_read_b128 v[134:137], v74 offset:32960
	ds_read_b128 v[156:159], v112
	ds_read_b128 v[160:163], v112 offset:64
	s_waitcnt lgkmcnt(1)
	v_mfma_f32_16x16x32_bf16 v[156:159], v[122:125], v[156:159], 0
	v_add_u32_e32 v121, v120, v118
	s_waitcnt lgkmcnt(0)
	v_mfma_f32_16x16x32_bf16 v[156:159], v[126:129], v[160:163], v[156:159]
	ds_read_b128 v[160:163], v112 offset:128
	s_waitcnt lgkmcnt(0)
	v_mfma_f32_16x16x32_bf16 v[156:159], v[130:133], v[160:163], v[156:159]
	ds_read_b128 v[160:163], v112 offset:192
	s_waitcnt lgkmcnt(0)
	v_mfma_f32_16x16x32_bf16 v[156:159], v[134:137], v[160:163], v[156:159]
	ds_read_b128 v[160:163], v111
	s_waitcnt lgkmcnt(0)
	v_mfma_f32_16x16x32_bf16 v[122:125], v[122:125], v[160:163], 0
	ds_read_b128 v[160:163], v111 offset:64
	s_waitcnt lgkmcnt(0)
	v_mfma_f32_16x16x32_bf16 v[122:125], v[126:129], v[160:163], v[122:125]
	ds_read_b128 v[126:129], v111 offset:128
	s_waitcnt lgkmcnt(0)
	v_mfma_f32_16x16x32_bf16 v[122:125], v[130:133], v[126:129], v[122:125]
	ds_read_b128 v[126:129], v111 offset:192
	s_waitcnt lgkmcnt(0)
	s_barrier
; #define LAS __attribute__((address_space(3)))
; __device__ __forceinline__ float bflo(unsigned u) { return __uint_as_float(u << 16); }
; template <bool RET>
; __device__ __forceinline__ void recur_item(ParamsK p, int l, int b, int h, int vs, LAS unsigned char* lds) {
;     ...
;             float qf[8] = {bflo(nq[i].x), bfhi(nq[i].x), bflo(nq[i].y), bfhi(nq[i].y), bflo(nq[i].z), bfhi(nq[i].z), bflo(nq[i].w), bfhi(nq[i].w)};
;             float kf[8] = {bflo(nk[i].x), bfhi(nk[i].x), bflo(nk[i].y), bfhi(nk[i].y), bflo(nk[i].z), bfhi(nk[i].z), bflo(nk[i].w), bfhi(nk[i].w)};
;             float qt[8], kt[8];
; #pragma unroll
;     ...
; #pragma unroll
;         for (int u = 0; u < 2; ++u) {
;             { const int vt = vb + 2 * u, swv = ((2 * vt + (r >> 3)) & 7) << 3; const LAS bf16_t* pp = Pm + (tm * 16 + r) * 72 + q * 8; const LAS bf16_t* vr = Vt + (vt * 16 + r) * 72;
;               acco[u] = __builtin_amdgcn_mfma_f32_16x16x32_bf16(*(const LAS bf16x8*)pp, *(const LAS bf16x8*)(vr + ((q * 8) ^ swv)), acco[u], 0, 0, 0);
;               acco[u] = __builtin_amdgcn_mfma_f32_16x16x32_bf16(*(const LAS bf16x8*)(pp + 32), *(const LAS bf16x8*)(vr + ((32 + q * 8) ^ swv)), acco[u], 0, 0, 0); }
; #pragma unroll
;             for (int j = 0; j < 4; ++j) oraw[(row0 + tm * 16 + q * 4 + j) * DM + ocol + (vb + 2 * u) * 16 + r] = acco[u][j];
;         }
;         {
;             const int swk = ((2 * w + (r >> 3)) & 7) << 3;
;             const bf16x8 ka0 = *(const LAS bf16x8*)(KhT + (16 * w + r) * 72 + ((q * 8) ^ swk)), ka1 = *(const LAS bf16x8*)(KhT + (16 * w + r) * 72 + ((32 + q * 8) ^ swk));
; #pragma unroll
;             for (int v2 = 0; v2 < 4; ++v2) {
;                 accS[v2] = accS[v2] * dec;
;                 { const int swv = ((2 * v2 + (r >> 3)) & 7) << 3; const LAS bf16_t* vr = Vt + (v2 * 16 + r) * 72;
;                   accS[v2] = __builtin_amdgcn_mfma_f32_16x16x32_bf16(ka0, *(const LAS bf16x8*)(vr + ((q * 8) ^ swv)), accS[v2], 0, 0, 0);
;                   accS[v2] = __builtin_amdgcn_mfma_f32_16x16x32_bf16(ka1, *(const LAS bf16x8*)(vr + ((32 + q * 8) ^ swv)), accS[v2], 0, 0, 0); }
;                 u32x2 ws; ws.x = cvt_pk_bf16(accS[v2][0], accS[v2][1]); ws.y = cvt_pk_bf16(accS[v2][2], accS[v2][3]);
;                 *(LAS u32x2*)(St + (v2 * 16 + r) * 136 + 16 * w + q * 4) = ws;
;             }
;         }
;         __syncthreads();
	v_mfma_f32_16x16x32_bf16 v[122:125], v[134:137], v[126:129], v[122:125]
	ds_read_b128 v[126:129], v102
	ds_read_b128 v[130:133], v102 offset:64
	ds_read_b128 v[134:137], v110
	s_waitcnt lgkmcnt(0)
	v_mfma_f32_16x16x32_bf16 v[134:137], v[126:129], v[134:137], v[156:159]
	s_nop 2
	ds_read_b128 v[156:159], v109
	s_waitcnt lgkmcnt(0)
	v_mfma_f32_16x16x32_bf16 v[134:137], v[130:133], v[156:159], v[134:137]
	v_lshl_add_u64 v[156:157], s[18:19], 0, v[80:81]
	v_add_co_u32_e64 v158, s[6:7], s6, v156
	s_nop 1
	v_addc_co_u32_e64 v159, s[6:7], 0, v157, s[6:7]
	s_mov_b32 s6, 0x23ea2000
	s_nop 0
	v_add_co_u32_e64 v160, s[6:7], s6, v156
	global_store_dword v[158:159], v134, off
	s_nop 0
	v_addc_co_u32_e64 v161, s[6:7], 0, v157, s[6:7]
	s_mov_b32 s6, 0x23ea4000
	s_nop 0
	v_add_co_u32_e64 v162, s[6:7], s6, v156
	global_store_dword v[160:161], v135, off
	s_nop 0
	v_addc_co_u32_e64 v163, s[6:7], 0, v157, s[6:7]
	s_mov_b32 s6, 0x23ea6000
	s_nop 0
	v_add_co_u32_e64 v156, s[6:7], s6, v156
	global_store_dword v[162:163], v136, off
	s_nop 0
	v_addc_co_u32_e64 v157, s[6:7], 0, v157, s[6:7]
	global_store_dword v[156:157], v137, off
	ds_read_b128 v[134:137], v103
	s_waitcnt lgkmcnt(0)
	v_mfma_f32_16x16x32_bf16 v[122:125], v[126:129], v[134:137], v[122:125]
	ds_read_b128 v[126:129], v104
	s_mov_b64 s[6:7], 0x80000
	v_lshl_add_u64 v[80:81], v[80:81], 0, s[6:7]
	s_waitcnt lgkmcnt(0)
	v_mfma_f32_16x16x32_bf16 v[122:125], v[130:133], v[126:129], v[122:125]
	s_nop 7
	global_store_dword v[158:159], v122, off offset:128
	global_store_dword v[160:161], v123, off offset:128
	global_store_dword v[162:163], v124, off offset:128
	global_store_dword v[156:157], v125, off offset:128
	ds_read_b128 v[122:125], v75
	ds_read_b128 v[126:129], v71
	ds_read_b128 v[130:133], v106
	s_waitcnt lgkmcnt(0)
	v_mfma_f32_16x16x32_bf16 v[18:21], v[122:125], v[130:133], v[18:21]
	ds_read_b128 v[130:133], v105
	s_waitcnt lgkmcnt(0)
	v_mfma_f32_16x16x32_bf16 v[18:21], v[126:129], v[130:133], v[18:21]
	s_nop 7
	v_cvt_pk_bf16_f32 v130, v18, v19
	v_cvt_pk_bf16_f32 v131, v20, v21
	ds_write_b64 v121, v[130:131]
	ds_read_b128 v[130:133], v101
	s_waitcnt lgkmcnt(0)
	v_mfma_f32_16x16x32_bf16 v[14:17], v[122:125], v[130:133], v[14:17]
	ds_read_b128 v[130:133], v100
	s_waitcnt lgkmcnt(0)
	v_mfma_f32_16x16x32_bf16 v[14:17], v[126:129], v[130:133], v[14:17]
	s_nop 7
	v_cvt_pk_bf16_f32 v130, v14, v15
	v_cvt_pk_bf16_f32 v131, v16, v17
	ds_write_b64 v108, v[130:131]
	ds_read_b128 v[130:133], v79
	s_waitcnt lgkmcnt(0)
	v_mfma_f32_16x16x32_bf16 v[6:9], v[122:125], v[130:133], v[6:9]
	ds_read_b128 v[130:133], v77
	s_waitcnt lgkmcnt(0)
	v_mfma_f32_16x16x32_bf16 v[6:9], v[126:129], v[130:133], v[6:9]
	s_nop 7
	v_cvt_pk_bf16_f32 v130, v6, v7
	v_cvt_pk_bf16_f32 v131, v8, v9
	ds_write_b64 v108, v[130:131] offset:4352
	ds_read_b128 v[96:99], v69
	s_waitcnt lgkmcnt(0)
	v_mfma_f32_16x16x32_bf16 v[2:5], v[122:125], v[96:99], v[2:5]
	ds_read_b128 v[96:99], v67
	s_waitcnt lgkmcnt(0)
	v_mfma_f32_16x16x32_bf16 v[2:5], v[126:129], v[96:99], v[2:5]
	s_nop 7
	v_cvt_pk_bf16_f32 v96, v2, v3
	v_cvt_pk_bf16_f32 v97, v4, v5
	ds_write_b64 v108, v[96:97] offset:8704
	s_waitcnt lgkmcnt(0)
	s_barrier
	s_cbranch_scc0 .LBB0_652
	s_waitcnt vmcnt(9)
	v_mul_f32_e32 v62, 0x3fb8aa3b, v62
	v_mul_f32_e32 v80, 0xbfb8aa3b, v58
	v_mul_f32_e32 v58, 0x3fb8aa3b, v58
	v_exp_f32_e32 v84, v62
	v_mul_f32_e32 v62, 0xbfb8aa3b, v59
	v_mul_f32_e32 v59, 0x3fb8aa3b, v59
	v_exp_f32_e32 v58, v58
	v_exp_f32_e32 v59, v59
	v_exp_f32_e32 v80, v80
	v_exp_f32_e32 v81, v62
	v_lshlrev_b32_e32 v82, 16, v46
	v_and_b32_e32 v83, 0xffff0000, v46
	v_pk_mul_f32 v[58:59], v[58:59], v[82:83]
	v_lshlrev_b32_e32 v82, 16, v42
	v_and_b32_e32 v83, 0xffff0000, v42
	v_mul_f32_e32 v42, 0x3fb8aa3b, v63
	v_pk_mul_f32 v[80:81], v[80:81], v[82:83]
	v_exp_f32_e32 v82, v42
	v_mul_f32_e32 v42, v80, v84
	v_cvt_pk_bf16_f32 v42, v42, s0
	ds_write_b16 v119, v42
	v_mul_f32_e32 v42, v81, v82
	v_cvt_pk_bf16_f32 v42, v42, s0
	ds_write_b16 v119, v42 offset:144
	v_mul_f32_e32 v42, 0xbfb8aa3b, v60
	v_exp_f32_e32 v62, v42
	v_mul_f32_e32 v42, 0x3fb8aa3b, v60
	v_exp_f32_e32 v60, v42
	v_mul_f32_e32 v42, 0x3fb8aa3b, v64
	v_exp_f32_e32 v64, v42
	v_mul_f32_e32 v42, 0xbfb8aa3b, v61
	v_mul_f32_e32 v46, 0x3fb8aa3b, v61
	v_exp_f32_e32 v61, v46
	v_exp_f32_e32 v63, v42
	v_lshlrev_b32_e32 v46, 16, v47
	v_and_b32_e32 v47, 0xffff0000, v47
	v_lshlrev_b32_e32 v42, 16, v43
	v_and_b32_e32 v43, 0xffff0000, v43
	v_pk_mul_f32 v[46:47], v[60:61], v[46:47]
	v_pk_mul_f32 v[60:61], v[62:63], v[42:43]
	v_mul_f32_e32 v42, 0x3fb8aa3b, v65
	v_exp_f32_e32 v65, v42
	v_mul_f32_e32 v42, v60, v64
	v_cvt_pk_bf16_f32 v42, v42, s0
	ds_write_b16 v119, v42 offset:288
	v_mul_f32_e32 v42, v61, v65
	v_cvt_pk_bf16_f32 v42, v42, s0
	v_mul_f32_e32 v43, 0x3fb8aa3b, v50
	ds_write_b16 v119, v42 offset:432
	v_mul_f32_e32 v42, 0xbfb8aa3b, v50
	v_exp_f32_e32 v50, v43
	v_mul_f32_e32 v43, 0x3fb8aa3b, v54
	v_exp_f32_e32 v54, v43
	v_mul_f32_e32 v43, 0xbfb8aa3b, v51
	v_mul_f32_e32 v51, 0x3fb8aa3b, v51
	v_exp_f32_e32 v51, v51
	v_exp_f32_e32 v42, v42
	v_exp_f32_e32 v43, v43
	v_lshlrev_b32_e32 v62, 16, v48
	v_and_b32_e32 v63, 0xffff0000, v48
	v_pk_mul_f32 v[50:51], v[50:51], v[62:63]
	v_lshlrev_b32_e32 v62, 16, v44
	v_and_b32_e32 v63, 0xffff0000, v44
	v_pk_mul_f32 v[62:63], v[42:43], v[62:63]
	v_mul_f32_e32 v42, 0x3fb8aa3b, v55
	v_exp_f32_e32 v55, v42
	v_mul_f32_e32 v42, v62, v54
	v_cvt_pk_bf16_f32 v42, v42, s0
	ds_write_b16 v119, v42 offset:576
	v_mul_f32_e32 v42, v63, v55
	v_cvt_pk_bf16_f32 v42, v42, s0
	v_mul_f32_e32 v43, 0x3fb8aa3b, v52
	ds_write_b16 v119, v42 offset:720
	v_mul_f32_e32 v42, 0xbfb8aa3b, v52
	v_exp_f32_e32 v52, v43
	v_mul_f32_e32 v43, 0x3fb8aa3b, v56
; #define LAS __attribute__((address_space(3)))
; __device__ __forceinline__ bf16_t f2bf(float f) { return (bf16_t)(cvt_pk_bf16(f, 0.f) & 0xffffu); }
; template <bool RET>
; __device__ __forceinline__ void recur_item(ParamsK p, int l, int b, int h, int vs, LAS unsigned char* lds) {
;     ...
;             float qf[8] = {bflo(nq[i].x), bfhi(nq[i].x), bflo(nq[i].y), bfhi(nq[i].y), bflo(nq[i].z), bfhi(nq[i].z), bflo(nq[i].w), bfhi(nq[i].w)};
;             float kf[8] = {bflo(nk[i].x), bfhi(nk[i].x), bflo(nk[i].y), bfhi(nk[i].y), bflo(nk[i].z), bfhi(nk[i].z), bflo(nk[i].w), bfhi(nk[i].w)};
;             float qt[8], kt[8];
; #pragma unroll
;             for (int j = 0; j < 8; ++j) { const float em = __expf(-bb[j]); qt[j] = qf[j] * __expf(bb[j]); kt[j] = kf[j] * em; KhT[(kv + j) * 72 + (t ^ (((kv >> 3) & 7) << 3))] = f2bf(kt[j] * __expf(bl[j])); }
;             u32x4 wq, wk;
;             wq.x = cvt_pk_bf16(qt[0], qt[1]); wq.y = cvt_pk_bf16(qt[2], qt[3]); wq.z = cvt_pk_bf16(qt[4], qt[5]); wq.w = cvt_pk_bf16(qt[6], qt[7]);
;             wk.x = cvt_pk_bf16(kt[0], kt[1]); wk.y = cvt_pk_bf16(kt[2], kt[3]); wk.z = cvt_pk_bf16(kt[4], kt[5]); wk.w = cvt_pk_bf16(kt[6], kt[7]);
;             *(LAS u32x4*)(Qt + t * 136 + kv) = wq; *(LAS u32x4*)(Kt + t * 136 + kv) = wk;
;         }
;         { const int t = tid >> 3, vv = (tid & 7) * 8; LAS bf16_t* vp = Vt + vv * 72 + (t ^ (((vv >> 3) & 7) << 3));
;             vp[0 * 72] = (bf16_t)(nv.x & 0xffffu); vp[1 * 72] = (bf16_t)(nv.x >> 16); vp[2 * 72] = (bf16_t)(nv.y & 0xffffu); vp[3 * 72] = (bf16_t)(nv.y >> 16);
;             vp[4 * 72] = (bf16_t)(nv.z & 0xffffu); vp[5 * 72] = (bf16_t)(nv.z >> 16); vp[6 * 72] = (bf16_t)(nv.w & 0xffffu); vp[7 * 72] = (bf16_t)(nv.w >> 16); }
;         const f32x4 dec = RET ? (f32x4){__expf(64.0f * lg), __expf(64.0f * lg), __expf(64.0f * lg), __expf(64.0f * lg)} : (f32x4){__expf(nd[0]), __expf(nd[1]), __expf(nd[2]), __expf(nd[3])};
;         if (c + 1 < 32) {
;             const size_t rn = row0 + 64;
; #pragma unroll
;             for (int i = 0; i < 2; ++i) { const int idx = tid + i * 512, t = idx >> 4, kv = (idx & 15) * 8;
;                 nq[i] = *(const u32x4*)(proj + (rn + t) * NIN + qcol + kv); nk[i] = *(const u32x4*)(proj + (rn + t) * NIN + kcol + kv); }
;             nv = *(const u32x4*)(proj + (rn + (tid >> 3)) * NIN + vcol + (tid & 7) * 8);
;             if (!RET) {
; #pragma unroll
	v_exp_f32_e32 v56, v43
	v_mul_f32_e32 v43, 0xbfb8aa3b, v53
	v_mul_f32_e32 v44, 0x3fb8aa3b, v53
	v_exp_f32_e32 v42, v42
	v_exp_f32_e32 v53, v44
	v_exp_f32_e32 v43, v43
	v_lshlrev_b32_e32 v48, 16, v49
	v_and_b32_e32 v49, 0xffff0000, v49
	v_lshlrev_b32_e32 v44, 16, v45
	v_and_b32_e32 v45, 0xffff0000, v45
	v_pk_mul_f32 v[48:49], v[52:53], v[48:49]
	v_pk_mul_f32 v[52:53], v[42:43], v[44:45]
	v_mul_f32_e32 v42, 0x3fb8aa3b, v57
	v_exp_f32_e32 v57, v42
	v_mul_f32_e32 v42, v52, v56
	v_cvt_pk_bf16_f32 v42, v42, s0
	ds_write_b16 v119, v42 offset:864
	v_mul_f32_e32 v42, v53, v57
	v_cvt_pk_bf16_f32 v42, v42, s0
	ds_write_b16 v119, v42 offset:1008
	v_cvt_pk_bf16_f32 v42, v58, v59
	v_cvt_pk_bf16_f32 v43, v46, v47
	v_cvt_pk_bf16_f32 v44, v50, v51
	v_cvt_pk_bf16_f32 v45, v48, v49
	v_cvt_pk_bf16_f32 v46, v80, v81
	v_cvt_pk_bf16_f32 v47, v60, v61
	v_cvt_pk_bf16_f32 v48, v62, v63
	v_cvt_pk_bf16_f32 v49, v52, v53
	ds_write_b128 v78, v[42:45] offset:32768
	ds_write_b128 v78, v[46:49] offset:50176
	v_mul_f32_e32 v42, 0xbfb8aa3b, v38
	v_mul_f32_e32 v38, 0x3fb8aa3b, v38
	v_mul_f32_e32 v43, 0xbfb8aa3b, v39
	v_mul_f32_e32 v39, 0x3fb8aa3b, v39
	v_exp_f32_e32 v38, v38
	v_exp_f32_e32 v39, v39
	v_exp_f32_e32 v42, v42
	v_exp_f32_e32 v43, v43
	v_lshlrev_b32_e32 v44, 16, v30
	v_and_b32_e32 v45, 0xffff0000, v30
	v_pk_mul_f32 v[38:39], v[38:39], v[44:45]
	v_lshlrev_b32_e32 v44, 16, v26
	v_and_b32_e32 v45, 0xffff0000, v26
	v_pk_mul_f32 v[42:43], v[42:43], v[44:45]
	v_mul_f32_e32 v30, 0x3fb8aa3b, v41
	v_mul_f32_e32 v26, v42, v84
	v_cvt_pk_bf16_f32 v26, v26, s0
	ds_write_b16 v117, v26
	v_mul_f32_e32 v26, v43, v82
	v_cvt_pk_bf16_f32 v26, v26, s0
	ds_write_b16 v117, v26 offset:144
	v_mul_f32_e32 v26, 0xbfb8aa3b, v40
	v_exp_f32_e32 v44, v26
	v_mul_f32_e32 v26, 0x3fb8aa3b, v40
	v_exp_f32_e32 v40, v26
	v_mul_f32_e32 v26, 0xbfb8aa3b, v41
	v_exp_f32_e32 v41, v30
	v_exp_f32_e32 v45, v26
	v_lshlrev_b32_e32 v30, 16, v31
	v_and_b32_e32 v31, 0xffff0000, v31
	v_lshlrev_b32_e32 v26, 16, v27
	v_and_b32_e32 v27, 0xffff0000, v27
	v_pk_mul_f32 v[30:31], v[40:41], v[30:31]
	v_pk_mul_f32 v[40:41], v[44:45], v[26:27]
	v_mul_f32_e32 v27, 0x3fb8aa3b, v34
	v_mul_f32_e32 v26, v40, v64
	v_cvt_pk_bf16_f32 v26, v26, s0
	ds_write_b16 v117, v26 offset:288
	v_mul_f32_e32 v26, v41, v65
	v_cvt_pk_bf16_f32 v26, v26, s0
	ds_write_b16 v117, v26 offset:432
	v_mul_f32_e32 v26, 0xbfb8aa3b, v34
	v_exp_f32_e32 v34, v27
	v_mul_f32_e32 v27, 0xbfb8aa3b, v35
	v_mul_f32_e32 v35, 0x3fb8aa3b, v35
	v_exp_f32_e32 v35, v35
	v_exp_f32_e32 v26, v26
	v_exp_f32_e32 v27, v27
	v_lshlrev_b32_e32 v44, 16, v32
	v_and_b32_e32 v45, 0xffff0000, v32
	v_pk_mul_f32 v[34:35], v[34:35], v[44:45]
	v_lshlrev_b32_e32 v44, 16, v28
	v_and_b32_e32 v45, 0xffff0000, v28
	v_pk_mul_f32 v[44:45], v[26:27], v[44:45]
	v_mul_f32_e32 v27, 0x3fb8aa3b, v36
	v_mul_f32_e32 v26, v44, v54
	v_cvt_pk_bf16_f32 v26, v26, s0
	ds_write_b16 v117, v26 offset:576
	v_mul_f32_e32 v26, v45, v55
	v_cvt_pk_bf16_f32 v26, v26, s0
	ds_write_b16 v117, v26 offset:720
	v_mul_f32_e32 v26, 0xbfb8aa3b, v36
	v_exp_f32_e32 v36, v27
	v_mul_f32_e32 v27, 0xbfb8aa3b, v37
	v_mul_f32_e32 v28, 0x3fb8aa3b, v37
	v_exp_f32_e32 v26, v26
	v_exp_f32_e32 v37, v28
	v_exp_f32_e32 v27, v27
	v_lshlrev_b32_e32 v32, 16, v33
	v_and_b32_e32 v33, 0xffff0000, v33
	v_lshlrev_b32_e32 v28, 16, v29
	v_and_b32_e32 v29, 0xffff0000, v29
	v_pk_mul_f32 v[32:33], v[36:37], v[32:33]
	v_pk_mul_f32 v[36:37], v[26:27], v[28:29]
	v_cvt_pk_bf16_f32 v27, v30, v31
	v_mul_f32_e32 v26, v36, v56
	v_cvt_pk_bf16_f32 v26, v26, s0
	ds_write_b16 v117, v26 offset:864
	v_mul_f32_e32 v26, v37, v57
	v_cvt_pk_bf16_f32 v26, v26, s0
	ds_write_b16 v117, v26 offset:1008
	v_cvt_pk_bf16_f32 v26, v38, v39
	v_cvt_pk_bf16_f32 v28, v34, v35
	v_cvt_pk_bf16_f32 v29, v32, v33
	v_cvt_pk_bf16_f32 v30, v42, v43
	v_cvt_pk_bf16_f32 v31, v40, v41
	v_cvt_pk_bf16_f32 v32, v44, v45
	v_cvt_pk_bf16_f32 v33, v36, v37
	ds_write_b128 v76, v[26:29] offset:32768
	ds_write_b128 v76, v[30:33] offset:50176
	ds_write_b16 v0, v22
	ds_write_b16_d16_hi v0, v22 offset:144
	ds_write_b16 v0, v23 offset:288
	ds_write_b16_d16_hi v0, v23 offset:432
	ds_write_b16 v0, v24 offset:576
	ds_write_b16_d16_hi v0, v24 offset:720
	ds_write_b16 v0, v25 offset:864
	ds_write_b16_d16_hi v0, v25 offset:1008
	s_waitcnt lgkmcnt(0)
	s_barrier
; __device__ __forceinline__ bf16_t f2bf(float f) { return (bf16_t)(cvt_pk_bf16(f, 0.f) & 0xffffu); }
; template <bool RET>
; __device__ __forceinline__ void recur_item(ParamsK p, int l, int b, int h, int vs, LAS unsigned char* lds) {
;     ...
;         const f32x4 dec = RET ? (f32x4){__expf(64.0f * lg), __expf(64.0f * lg), __expf(64.0f * lg), __expf(64.0f * lg)} : (f32x4){__expf(nd[0]), __expf(nd[1]), __expf(nd[2]), __expf(nd[3])};
;     ...
;         const int tm = w >> 1, vb = w & 1;
; #pragma unroll
;         for (int s2 = 0; s2 < 2; ++s2) {
;             const int sn = (w & 1) * 2 + s2;
;             f32x4 sc = mma_lds((f32x4){0.f, 0.f, 0.f, 0.f}, Qt + tm * 16 * 136, 136, Kt + sn * 16 * 136, 136, 128, lane);
; #pragma unroll
;             for (int j = 0; j < 4; ++j) if (sn > tm || (sn == tm && r > q * 4 + j)) sc[j] = 0.f;
; #pragma unroll
;             for (int j = 0; j < 4; ++j) Pm[(tm * 16 + q * 4 + j) * 72 + sn * 16 + r] = f2bf(sc[j]);
;         }
;         f32x4 acco[2];
; #pragma unroll
;         for (int u = 0; u < 2; ++u) acco[u] = mma_lds((f32x4){0.f, 0.f, 0.f, 0.f}, Qt + tm * 16 * 136, 136, St + (vb + 2 * u) * 16 * 136, 136, 128, lane);
;         __syncthreads();
	ds_read_b128 v[22:25], v74 offset:32768
	ds_read_b128 v[26:29], v74 offset:32832
	ds_read_b128 v[30:33], v116 offset:50176
	ds_read_b128 v[34:37], v116 offset:50240
	s_waitcnt lgkmcnt(1)
	v_mfma_f32_16x16x32_bf16 v[22:25], v[22:25], v[30:33], 0
	ds_read_b128 v[30:33], v74 offset:32896
	v_mov_b32_e32 v0, s53
	s_waitcnt vmcnt(8)
	v_mul_f32_e32 v10, 0x3fb8aa3b, v10
	s_waitcnt lgkmcnt(1)
	v_mfma_f32_16x16x32_bf16 v[22:25], v[26:29], v[34:37], v[22:25]
	ds_read_b128 v[26:29], v74 offset:32960
	ds_read_b128 v[34:37], v116 offset:50304
	ds_read_b128 v[38:41], v116 offset:50368
	v_exp_f32_e32 v58, v10
	v_mul_f32_e32 v10, 0x3fb8aa3b, v11
	s_waitcnt lgkmcnt(1)
	v_mfma_f32_16x16x32_bf16 v[22:25], v[30:33], v[34:37], v[22:25]
	v_exp_f32_e32 v59, v10
	v_mul_f32_e32 v10, 0x3fb8aa3b, v12
	v_exp_f32_e32 v60, v10
	s_waitcnt lgkmcnt(0)
	v_mfma_f32_16x16x32_bf16 v[22:25], v[26:29], v[38:41], v[22:25]
	v_or_b32_e32 v72, v68, v72
	v_lshlrev_b32_e32 v52, 2, v107
	v_mov_b32_e32 v53, v1
	v_pk_mul_f32 v[18:19], v[58:59], v[18:19]
	v_pk_mul_f32 v[14:15], v[58:59], v[14:15]
	s_nop 2
	v_cndmask_b32_e64 v0, v22, v0, s[4:5]
	v_cndmask_b32_e64 v22, v23, 0, s[22:23]
	v_cvt_pk_bf16_f32 v0, v0, s0
	v_cndmask_b32_e64 v23, v24, 0, s[24:25]
	ds_write_b16 v115, v0
	v_cvt_pk_bf16_f32 v0, v22, s0
	v_cndmask_b32_e64 v24, v25, 0, s[26:27]
	ds_write_b16 v115, v0 offset:144
	v_cvt_pk_bf16_f32 v0, v23, s0
	ds_write_b16 v115, v0 offset:288
	v_cvt_pk_bf16_f32 v0, v24, s0
	ds_write_b16 v115, v0 offset:432
	ds_read_b128 v[22:25], v74 offset:32768
	ds_read_b128 v[26:29], v74 offset:32832
	ds_read_b128 v[30:33], v114 offset:50176
	ds_read_b128 v[34:37], v114 offset:50240
	s_waitcnt lgkmcnt(1)
	v_mfma_f32_16x16x32_bf16 v[22:25], v[22:25], v[30:33], 0
	ds_read_b128 v[30:33], v74 offset:32896
	v_mov_b32_e32 v0, s53
	s_lshl_b32 s4, s44, 2
	s_waitcnt lgkmcnt(1)
	v_mfma_f32_16x16x32_bf16 v[22:25], v[26:29], v[34:37], v[22:25]
	ds_read_b128 v[26:29], v74 offset:32960
	ds_read_b128 v[34:37], v114 offset:50304
	ds_read_b128 v[38:41], v114 offset:50368
	s_add_u32 s4, s18, s4
	s_addc_u32 s5, s19, 0
	s_waitcnt lgkmcnt(1)
	v_mfma_f32_16x16x32_bf16 v[22:25], v[30:33], v[34:37], v[22:25]
	v_mul_f32_e64 v6, v58, v6
	v_mul_f32_e64 v7, v59, v7
	v_pk_mul_f32 v[2:3], v[58:59], v[2:3]
	s_add_i32 s6, s16, s35
	s_waitcnt lgkmcnt(0)
	v_mfma_f32_16x16x32_bf16 v[22:25], v[26:29], v[38:41], v[22:25]
	s_ashr_i32 s7, s6, 31
	s_lshl_b64 s[6:7], s[6:7], 19
	s_nop 5
	v_cndmask_b32_e32 v0, v22, v0, vcc
	v_cndmask_b32_e64 v22, v23, 0, s[8:9]
	v_cvt_pk_bf16_f32 v0, v0, s0
	v_cndmask_b32_e64 v23, v24, 0, s[10:11]
	ds_write_b16 v113, v0
	v_cvt_pk_bf16_f32 v0, v22, s0
	v_cndmask_b32_e64 v24, v25, 0, s[12:13]
	ds_write_b16 v113, v0 offset:144
	v_cvt_pk_bf16_f32 v0, v23, s0
	ds_write_b16 v113, v0 offset:288
	v_cvt_pk_bf16_f32 v0, v24, s0
	ds_write_b16 v113, v0 offset:432
	ds_read_b128 v[22:25], v74 offset:32768
	ds_read_b128 v[26:29], v74 offset:32832
	ds_read_b128 v[30:33], v112
	ds_read_b128 v[34:37], v74 offset:32896
	ds_read_b128 v[38:41], v112 offset:64
	s_waitcnt lgkmcnt(2)
	v_mfma_f32_16x16x32_bf16 v[30:33], v[22:25], v[30:33], 0
	ds_read_b128 v[42:45], v74 offset:32960
	ds_read_b128 v[46:49], v112 offset:128
	v_lshlrev_b32_e32 v0, 2, v70
	v_lshl_add_u64 v[50:51], s[4:5], 0, v[0:1]
	s_waitcnt lgkmcnt(2)
	v_mfma_f32_16x16x32_bf16 v[30:33], v[26:29], v[38:41], v[30:33]
	ds_read_b128 v[38:41], v112 offset:192
	v_lshl_add_u64 v[50:51], v[50:51], 0, v[52:53]
	v_lshl_add_u64 v[54:55], v[50:51], 0, s[64:65]
	s_waitcnt lgkmcnt(1)
	v_mfma_f32_16x16x32_bf16 v[30:33], v[34:37], v[46:49], v[30:33]
	ds_read_b128 v[46:49], v111
	s_mov_b64 s[4:5], 0x23ea0080
	v_lshl_add_u64 v[56:57], v[50:51], 0, s[4:5]
	s_waitcnt lgkmcnt(1)
	v_mfma_f32_16x16x32_bf16 v[30:33], v[42:45], v[38:41], v[30:33]
	ds_read_b128 v[38:41], v111 offset:64
	s_mov_b64 s[4:5], 0xf80000
	s_waitcnt lgkmcnt(1)
	v_mfma_f32_16x16x32_bf16 v[22:25], v[22:25], v[46:49], 0
	s_waitcnt lgkmcnt(0)
	v_mfma_f32_16x16x32_bf16 v[22:25], v[26:29], v[38:41], v[22:25]
	ds_read_b128 v[26:29], v111 offset:128
	ds_read_b128 v[38:41], v111 offset:192
	s_waitcnt lgkmcnt(0)
	s_barrier
; #define LAS __attribute__((address_space(3)))
; template <bool RET>
; __device__ __forceinline__ void recur_item(ParamsK p, int l, int b, int h, int vs, LAS unsigned char* lds) {
;     ...
; #pragma unroll
;         for (int u = 0; u < 2; ++u) {
;             { const int vt = vb + 2 * u, swv = ((2 * vt + (r >> 3)) & 7) << 3; const LAS bf16_t* pp = Pm + (tm * 16 + r) * 72 + q * 8; const LAS bf16_t* vr = Vt + (vt * 16 + r) * 72;
;               acco[u] = __builtin_amdgcn_mfma_f32_16x16x32_bf16(*(const LAS bf16x8*)pp, *(const LAS bf16x8*)(vr + ((q * 8) ^ swv)), acco[u], 0, 0, 0);
;               acco[u] = __builtin_amdgcn_mfma_f32_16x16x32_bf16(*(const LAS bf16x8*)(pp + 32), *(const LAS bf16x8*)(vr + ((32 + q * 8) ^ swv)), acco[u], 0, 0, 0); }
; #pragma unroll
;             for (int j = 0; j < 4; ++j) oraw[(row0 + tm * 16 + q * 4 + j) * DM + ocol + (vb + 2 * u) * 16 + r] = acco[u][j];
;         }
;         {
;             const int swk = ((2 * w + (r >> 3)) & 7) << 3;
;             const bf16x8 ka0 = *(const LAS bf16x8*)(KhT + (16 * w + r) * 72 + ((q * 8) ^ swk)), ka1 = *(const LAS bf16x8*)(KhT + (16 * w + r) * 72 + ((32 + q * 8) ^ swk));
; #pragma unroll
;             for (int v2 = 0; v2 < 4; ++v2) {
;                 accS[v2] = accS[v2] * dec;
;                 { const int swv = ((2 * v2 + (r >> 3)) & 7) << 3; const LAS bf16_t* vr = Vt + (v2 * 16 + r) * 72;
;                   accS[v2] = __builtin_amdgcn_mfma_f32_16x16x32_bf16(ka0, *(const LAS bf16x8*)(vr + ((q * 8) ^ swv)), accS[v2], 0, 0, 0);
;                   accS[v2] = __builtin_amdgcn_mfma_f32_16x16x32_bf16(ka1, *(const LAS bf16x8*)(vr + ((32 + q * 8) ^ swv)), accS[v2], 0, 0, 0); }
;                 u32x2 ws; ws.x = cvt_pk_bf16(accS[v2][0], accS[v2][1]); ws.y = cvt_pk_bf16(accS[v2][2], accS[v2][3]);
;                 *(LAS u32x2*)(St + (v2 * 16 + r) * 136 + 16 * w + q * 4) = ws;
;             }
;         }
;         __syncthreads();
;     }
;     float* so = p->out + (RET ? O_PRET : O_PGLA) + ((size_t)(l * NB + b) * NH + h) * 128 * DV;
; #pragma unroll
;     for (int v2 = 0; v2 < 4; ++v2)
; #pragma unroll
;         for (int j = 0; j < 4; ++j) so[(size_t)(16 * w + q * 4 + j) * DV + vs * 64 + v2 * 16 + r] = accS[v2][j];
;     __syncthreads();
	ds_read_b128 v[46:49], v102
	v_mfma_f32_16x16x32_bf16 v[22:25], v[34:37], v[26:29], v[22:25]
	ds_read_b128 v[26:29], v102 offset:64
	ds_read_b128 v[34:37], v110
	v_mfma_f32_16x16x32_bf16 v[22:25], v[42:45], v[38:41], v[22:25]
	v_mul_f32_e32 v38, 0x3fb8aa3b, v13
	ds_read_b128 v[10:13], v109
	v_exp_f32_e32 v61, v38
	s_waitcnt lgkmcnt(1)
	v_mfma_f32_16x16x32_bf16 v[30:33], v[46:49], v[34:37], v[30:33]
	v_lshl_add_u64 v[34:35], v[72:73], 0, s[20:21]
	v_lshlrev_b64 v[62:63], 13, v[34:35]
	v_pk_mul_f32 v[20:21], v[60:61], v[20:21]
	s_waitcnt lgkmcnt(0)
	v_mfma_f32_16x16x32_bf16 v[10:13], v[26:29], v[10:13], v[30:33]
	v_mul_f32_e64 v16, v60, v16
	v_mul_f32_e64 v17, v61, v17
	v_pk_mul_f32 v[8:9], v[60:61], v[8:9]
	v_pk_mul_f32 v[4:5], v[60:61], v[4:5]
	v_lshl_add_u64 v[30:31], v[54:55], 0, v[62:63]
	v_lshl_add_u64 v[64:65], v[30:31], 0, s[4:5]
	s_mov_b32 s4, 0xf80000
	v_add_co_u32_e32 v30, vcc, s4, v30
	s_mov_b64 s[4:5], 0xf82000
	s_nop 0
	v_addc_co_u32_e32 v31, vcc, 0, v31, vcc
	global_store_dword v[30:31], v10, off
	ds_read_b128 v[30:33], v75
	v_lshl_add_u64 v[72:73], v[62:63], 0, s[4:5]
	v_lshl_add_u64 v[34:35], v[54:55], 0, v[72:73]
	global_store_dword v[34:35], v11, off
	ds_read_b128 v[34:37], v71
	ds_read_b128 v[38:41], v106
	ds_read_b128 v[42:45], v105
	s_waitcnt lgkmcnt(1)
	v_mfma_f32_16x16x32_bf16 v[18:21], v[30:33], v[38:41], v[18:21]
	s_mov_b64 s[4:5], 0xf84000
	v_lshl_add_u64 v[74:75], v[62:63], 0, s[4:5]
	v_lshl_add_u64 v[10:11], v[54:55], 0, v[74:75]
	s_waitcnt lgkmcnt(0)
	v_mfma_f32_16x16x32_bf16 v[18:21], v[34:37], v[42:45], v[18:21]
	global_store_dword v[10:11], v12, off
	ds_read_b128 v[38:41], v103
	ds_read_b128 v[50:53], v104
	s_mov_b64 s[4:5], 0xf86000
	s_waitcnt lgkmcnt(1)
	v_mfma_f32_16x16x32_bf16 v[22:25], v[46:49], v[38:41], v[22:25]
	s_nop 1
	v_cvt_pk_bf16_f32 v10, v18, v19
	v_cvt_pk_bf16_f32 v11, v20, v21
	ds_write_b64 v121, v[10:11]
	ds_read_b128 v[42:45], v101
	ds_read_b128 v[38:41], v100
	s_waitcnt lgkmcnt(1)
	v_mfma_f32_16x16x32_bf16 v[14:17], v[30:33], v[42:45], v[14:17]
	v_lshl_add_u64 v[42:43], v[62:63], 0, s[4:5]
	v_lshl_add_u64 v[10:11], v[54:55], 0, v[42:43]
	global_store_dword v[10:11], v13, off
	s_waitcnt lgkmcnt(0)
	v_mfma_f32_16x16x32_bf16 v[10:13], v[34:37], v[38:41], v[14:17]
	v_mfma_f32_16x16x32_bf16 v[22:25], v[26:29], v[50:53], v[22:25]
	s_nop 6
	v_cvt_pk_bf16_f32 v14, v10, v11
	v_cvt_pk_bf16_f32 v15, v12, v13
	ds_write_b64 v108, v[14:15]
	ds_read_b128 v[14:17], v79
	ds_read_b128 v[26:29], v77
	s_waitcnt lgkmcnt(1)
	v_mfma_f32_16x16x32_bf16 v[6:9], v[30:33], v[14:17], v[6:9]
	v_lshl_add_u64 v[14:15], v[56:57], 0, v[72:73]
	global_store_dword v[14:15], v23, off
	global_store_dword v[64:65], v22, off offset:128
	s_waitcnt lgkmcnt(0)
	v_mfma_f32_16x16x32_bf16 v[6:9], v[34:37], v[26:29], v[6:9]
	v_lshl_add_u64 v[22:23], v[56:57], 0, v[74:75]
	global_store_dword v[22:23], v24, off
	s_nop 5
	v_cvt_pk_bf16_f32 v14, v6, v7
	v_cvt_pk_bf16_f32 v15, v8, v9
	ds_write_b64 v108, v[14:15] offset:4352
	ds_read_b128 v[14:17], v69
	ds_read_b128 v[26:29], v67
	s_waitcnt lgkmcnt(1)
	v_mfma_f32_16x16x32_bf16 v[2:5], v[30:33], v[14:17], v[2:5]
	v_lshl_add_u64 v[14:15], v[56:57], 0, v[42:43]
	global_store_dword v[14:15], v25, off
	s_waitcnt lgkmcnt(0)
	v_mfma_f32_16x16x32_bf16 v[2:5], v[34:37], v[26:29], v[2:5]
	s_nop 7
	v_cvt_pk_bf16_f32 v14, v2, v3
	v_cvt_pk_bf16_f32 v15, v4, v5
	ds_write_b64 v108, v[14:15] offset:8704
	s_waitcnt lgkmcnt(0)
	s_barrier
	s_load_dwordx2 s[4:5], s[0:1], 0xf0
	v_or_b32_e32 v14, v68, v66
	v_ashrrev_i32_e32 v15, 31, v14
	v_or_b32_e32 v24, 1, v14
	v_lshlrev_b64 v[22:23], 10, v[14:15]
	s_waitcnt lgkmcnt(0)
	s_add_u32 s4, s4, s6
	s_addc_u32 s5, s5, s7
	s_lshl_b32 s6, s40, 17
	s_add_u32 s4, s4, s6
	s_addc_u32 s5, s5, 0
	s_lshl_b32 s6, s41, 2
	s_add_u32 s4, s4, s6
	s_addc_u32 s5, s5, 0
	v_lshl_add_u64 v[16:17], s[4:5], 0, v[0:1]
	s_mov_b64 s[4:5], 0x4140000
	v_lshl_add_u64 v[16:17], v[16:17], 0, s[4:5]
	v_ashrrev_i32_e32 v25, 31, v24
	v_lshl_add_u64 v[22:23], v[16:17], 0, v[22:23]
	v_lshlrev_b64 v[24:25], 10, v[24:25]
	global_store_dword v[22:23], v18, off
	v_lshl_add_u64 v[24:25], v[16:17], 0, v[24:25]
	v_or_b32_e32 v18, 2, v14
	v_or_b32_e32 v14, 3, v14
	global_store_dword v[24:25], v19, off
	v_ashrrev_i32_e32 v19, 31, v18
	v_ashrrev_i32_e32 v15, 31, v14
	v_lshlrev_b64 v[18:19], 10, v[18:19]
	v_lshlrev_b64 v[14:15], 10, v[14:15]
	v_lshl_add_u64 v[18:19], v[16:17], 0, v[18:19]
	v_lshl_add_u64 v[14:15], v[16:17], 0, v[14:15]
	global_store_dword v[18:19], v20, off
	global_store_dword v[14:15], v21, off
	global_store_dword v[22:23], v10, off offset:64
	global_store_dword v[24:25], v11, off offset:64
	global_store_dword v[18:19], v12, off offset:64
	global_store_dword v[14:15], v13, off offset:64
	global_store_dword v[22:23], v6, off offset:128
	global_store_dword v[24:25], v7, off offset:128
	global_store_dword v[18:19], v8, off offset:128
	global_store_dword v[14:15], v9, off offset:128
	global_store_dword v[22:23], v2, off offset:192
	global_store_dword v[24:25], v3, off offset:192
	global_store_dword v[18:19], v4, off offset:192
	global_store_dword v[14:15], v5, off offset:192
	s_barrier
	s_branch .LBB0_637
